# v21: v19 + CMP1 hid stores write-through (sc0 sc1), no L2 writeback/invalidate in the CMP1->CMP2 handoff
# speedup vs baseline: 1.0106x; 1.0043x over previous
.LBB0_561:
	s_and_b64 s[2:3], s[4:5], exec
	v_readlane_b32 s4, v255, 61
	v_mov_b32_e32 v64, v166
	v_readlane_b32 s12, v254, 5
	v_readlane_b32 s13, v254, 6
	v_readlane_b32 s14, v254, 7
	v_readlane_b32 s15, v254, 8
	v_readlane_b32 s16, v254, 9
	v_readlane_b32 s17, v254, 10
	s_waitcnt lgkmcnt(0)
	s_barrier
	v_readlane_b32 s18, v254, 11
	v_and_b32_e32 v65, 31, v64
	v_readlane_b32 s19, v254, 12
	s_mov_b64 s[12:13], s[16:17]
	v_readlane_b32 s5, v255, 62
	s_mov_b64 s[14:15], s[18:19]
	v_or3_b32 v66, v65, v174, s0
	s_cselect_b32 s5, s13, s15
	s_cselect_b32 s4, s12, s14
	v_lshlrev_b32_e32 v68, 2, v66
	global_load_dword v69, v68, s[4:5]
	v_readlane_b32 s36, v254, 13
	v_readlane_b32 s48, v254, 25
	v_readlane_b32 s49, v254, 26
	v_readlane_b32 s50, v254, 27
	v_readlane_b32 s51, v254, 28
	v_readlane_b32 s2, v255, 12
	s_cselect_b32 s1, s49, s51
	s_cselect_b32 s0, s48, s50
	s_and_b32 s2, s2, 30
	v_lshrrev_b32_e32 v64, 3, v64
	v_add_lshl_u32 v67, v172, s2, 6
	v_mov_b32_e32 v65, 0
	v_and_or_b32 v70, v64, 4, v67
	v_lshlrev_b32_e32 v64, 1, v66
	v_lshl_add_u64 v[66:67], s[0:1], 0, v[64:65]
	v_mul_u32_u24_e32 v64, 0x280, v70
	v_lshl_add_u64 v[64:65], v[66:67], 0, v[64:65]
	v_readlane_b32 s6, v255, 63
	v_readlane_b32 s7, v254, 0
	global_load_dword v68, v68, s[4:5] offset:128
	v_readlane_b32 s8, v254, 1
	v_readlane_b32 s9, v254, 2
	s_movk_i32 s2, 0x1000
	v_readlane_b32 s10, v254, 3
	v_readlane_b32 s11, v254, 4
	v_readlane_b32 s37, v254, 14
	v_readlane_b32 s38, v254, 15
	v_readlane_b32 s39, v254, 16
	v_readlane_b32 s40, v254, 17
	v_readlane_b32 s41, v254, 18
	v_readlane_b32 s42, v254, 19
	v_readlane_b32 s43, v254, 20
	v_readlane_b32 s44, v254, 21
	v_readlane_b32 s45, v254, 22
	v_readlane_b32 s46, v254, 23
	v_readlane_b32 s47, v254, 24
	s_waitcnt vmcnt(0)
	s_mov_b32 s3, 0
	s_mov_b32 s2, 0x1400
	v_lshl_add_u64 v[200:201], v[64:65], 0, s[2:3]
	s_mov_b32 s2, 0x2800
	v_lshl_add_u64 v[202:203], v[64:65], 0, s[2:3]
	s_mov_b32 s2, 0x3c00
	v_lshl_add_u64 v[204:205], v[64:65], 0, s[2:3]
	s_mov_b32 s2, 0x5000
	v_lshl_add_u64 v[206:207], v[64:65], 0, s[2:3]
	s_mov_b32 s2, 0x6400
	v_lshl_add_u64 v[208:209], v[64:65], 0, s[2:3]
	s_mov_b32 s2, 0x7800
	v_lshl_add_u64 v[210:211], v[64:65], 0, s[2:3]
	s_mov_b32 s2, 0x8c00
	v_lshl_add_u64 v[212:213], v[64:65], 0, s[2:3]
	v_add_f32_e32 v48, v48, v69
	v_add_f32_e32 v49, v49, v69
	v_add_f32_e32 v50, v50, v69
	v_add_f32_e32 v51, v51, v69
	v_mul_f32_e32 v80, 0xbfb8aa3b, v48
	v_mul_f32_e32 v81, 0xbfb8aa3b, v49
	v_mul_f32_e32 v82, 0xbfb8aa3b, v50
	v_mul_f32_e32 v83, 0xbfb8aa3b, v51
	v_exp_f32_e32 v80, v80
	v_exp_f32_e32 v81, v81
	v_exp_f32_e32 v82, v82
	v_exp_f32_e32 v83, v83
	v_add_f32_e32 v80, 1.0, v80
	v_add_f32_e32 v81, 1.0, v81
	v_add_f32_e32 v82, 1.0, v82
	v_add_f32_e32 v83, 1.0, v83
	v_rcp_f32_e32 v80, v80
	v_rcp_f32_e32 v81, v81
	v_rcp_f32_e32 v82, v82
	v_rcp_f32_e32 v83, v83
	v_mul_f32_e32 v48, v48, v80
	v_mul_f32_e32 v49, v49, v81
	v_mul_f32_e32 v50, v50, v82
	v_mul_f32_e32 v51, v51, v83
	v_cvt_pk_bf16_f32 v84, v48, v49
	v_cvt_pk_bf16_f32 v85, v50, v51
	global_store_short v[64:65], v84, off sc0 sc1
	global_store_short_d16_hi v[64:65], v84, off offset:640 sc0 sc1
	global_store_short v[64:65], v85, off offset:1280 sc0 sc1
	global_store_short_d16_hi v[64:65], v85, off offset:1920 sc0 sc1
	v_add_f32_e32 v52, v52, v69
	v_add_f32_e32 v53, v53, v69
	v_add_f32_e32 v54, v54, v69
	v_add_f32_e32 v55, v55, v69
	v_mul_f32_e32 v80, 0xbfb8aa3b, v52
	v_mul_f32_e32 v81, 0xbfb8aa3b, v53
	v_mul_f32_e32 v82, 0xbfb8aa3b, v54
	v_mul_f32_e32 v83, 0xbfb8aa3b, v55
	v_exp_f32_e32 v80, v80
	v_exp_f32_e32 v81, v81
	v_exp_f32_e32 v82, v82
	v_exp_f32_e32 v83, v83
	v_add_f32_e32 v80, 1.0, v80
	v_add_f32_e32 v81, 1.0, v81
	v_add_f32_e32 v82, 1.0, v82
	v_add_f32_e32 v83, 1.0, v83
	v_rcp_f32_e32 v80, v80
	v_rcp_f32_e32 v81, v81
	v_rcp_f32_e32 v82, v82
	v_rcp_f32_e32 v83, v83
	v_mul_f32_e32 v52, v52, v80
	v_mul_f32_e32 v53, v53, v81
	v_mul_f32_e32 v54, v54, v82
	v_mul_f32_e32 v55, v55, v83
	v_cvt_pk_bf16_f32 v86, v52, v53
	v_cvt_pk_bf16_f32 v87, v54, v55
	global_store_short v[200:201], v86, off sc0 sc1
	global_store_short_d16_hi v[200:201], v86, off offset:640 sc0 sc1
	global_store_short v[200:201], v87, off offset:1280 sc0 sc1
	global_store_short_d16_hi v[200:201], v87, off offset:1920 sc0 sc1
	v_add_f32_e32 v56, v56, v69
	v_add_f32_e32 v57, v57, v69
	v_add_f32_e32 v58, v58, v69
	v_add_f32_e32 v59, v59, v69
	v_mul_f32_e32 v80, 0xbfb8aa3b, v56
	v_mul_f32_e32 v81, 0xbfb8aa3b, v57
	v_mul_f32_e32 v82, 0xbfb8aa3b, v58
	v_mul_f32_e32 v83, 0xbfb8aa3b, v59
	v_exp_f32_e32 v80, v80
	v_exp_f32_e32 v81, v81
	v_exp_f32_e32 v82, v82
	v_exp_f32_e32 v83, v83
	v_add_f32_e32 v80, 1.0, v80
	v_add_f32_e32 v81, 1.0, v81
	v_add_f32_e32 v82, 1.0, v82
	v_add_f32_e32 v83, 1.0, v83
	v_rcp_f32_e32 v80, v80
	v_rcp_f32_e32 v81, v81
	v_rcp_f32_e32 v82, v82
	v_rcp_f32_e32 v83, v83
	v_mul_f32_e32 v56, v56, v80
	v_mul_f32_e32 v57, v57, v81
	v_mul_f32_e32 v58, v58, v82
	v_mul_f32_e32 v59, v59, v83
	v_cvt_pk_bf16_f32 v88, v56, v57
	v_cvt_pk_bf16_f32 v89, v58, v59
	global_store_short v[202:203], v88, off sc0 sc1
	global_store_short_d16_hi v[202:203], v88, off offset:640 sc0 sc1
	global_store_short v[202:203], v89, off offset:1280 sc0 sc1
	global_store_short_d16_hi v[202:203], v89, off offset:1920 sc0 sc1
	v_add_f32_e32 v60, v60, v69
	v_add_f32_e32 v61, v61, v69
	v_add_f32_e32 v62, v62, v69
	v_add_f32_e32 v63, v63, v69
	v_mul_f32_e32 v80, 0xbfb8aa3b, v60
	v_mul_f32_e32 v81, 0xbfb8aa3b, v61
	v_mul_f32_e32 v82, 0xbfb8aa3b, v62
	v_mul_f32_e32 v83, 0xbfb8aa3b, v63
	v_exp_f32_e32 v80, v80
	v_exp_f32_e32 v81, v81
	v_exp_f32_e32 v82, v82
	v_exp_f32_e32 v83, v83
	v_add_f32_e32 v80, 1.0, v80
	v_add_f32_e32 v81, 1.0, v81
	v_add_f32_e32 v82, 1.0, v82
	v_add_f32_e32 v83, 1.0, v83
	v_rcp_f32_e32 v80, v80
	v_rcp_f32_e32 v81, v81
	v_rcp_f32_e32 v82, v82
	v_rcp_f32_e32 v83, v83
	v_mul_f32_e32 v60, v60, v80
	v_mul_f32_e32 v61, v61, v81
	v_mul_f32_e32 v62, v62, v82
	v_mul_f32_e32 v63, v63, v83
	v_cvt_pk_bf16_f32 v90, v60, v61
	v_cvt_pk_bf16_f32 v91, v62, v63
	global_store_short v[204:205], v90, off sc0 sc1
	global_store_short_d16_hi v[204:205], v90, off offset:640 sc0 sc1
	global_store_short v[204:205], v91, off offset:1280 sc0 sc1
	global_store_short_d16_hi v[204:205], v91, off offset:1920 sc0 sc1
	v_add_f32_e32 v32, v32, v68
	v_add_f32_e32 v33, v33, v68
	v_add_f32_e32 v34, v34, v68
	v_add_f32_e32 v35, v35, v68
	v_mul_f32_e32 v80, 0xbfb8aa3b, v32
	v_mul_f32_e32 v81, 0xbfb8aa3b, v33
	v_mul_f32_e32 v82, 0xbfb8aa3b, v34
	v_mul_f32_e32 v83, 0xbfb8aa3b, v35
	v_exp_f32_e32 v80, v80
	v_exp_f32_e32 v81, v81
	v_exp_f32_e32 v82, v82
	v_exp_f32_e32 v83, v83
	v_add_f32_e32 v80, 1.0, v80
	v_add_f32_e32 v81, 1.0, v81
	v_add_f32_e32 v82, 1.0, v82
	v_add_f32_e32 v83, 1.0, v83
	v_rcp_f32_e32 v80, v80
	v_rcp_f32_e32 v81, v81
	v_rcp_f32_e32 v82, v82
	v_rcp_f32_e32 v83, v83
	v_mul_f32_e32 v32, v32, v80
	v_mul_f32_e32 v33, v33, v81
	v_mul_f32_e32 v34, v34, v82
	v_mul_f32_e32 v35, v35, v83
	v_cvt_pk_bf16_f32 v84, v32, v33
	v_cvt_pk_bf16_f32 v85, v34, v35
	global_store_short v[64:65], v84, off offset:64 sc0 sc1
	global_store_short_d16_hi v[64:65], v84, off offset:704 sc0 sc1
	global_store_short v[64:65], v85, off offset:1344 sc0 sc1
	global_store_short_d16_hi v[64:65], v85, off offset:1984 sc0 sc1
	v_add_f32_e32 v36, v36, v68
	v_add_f32_e32 v37, v37, v68
	v_add_f32_e32 v38, v38, v68
	v_add_f32_e32 v39, v39, v68
	v_mul_f32_e32 v80, 0xbfb8aa3b, v36
	v_mul_f32_e32 v81, 0xbfb8aa3b, v37
	v_mul_f32_e32 v82, 0xbfb8aa3b, v38
	v_mul_f32_e32 v83, 0xbfb8aa3b, v39
	v_exp_f32_e32 v80, v80
	v_exp_f32_e32 v81, v81
	v_exp_f32_e32 v82, v82
	v_exp_f32_e32 v83, v83
	v_add_f32_e32 v80, 1.0, v80
	v_add_f32_e32 v81, 1.0, v81
	v_add_f32_e32 v82, 1.0, v82
	v_add_f32_e32 v83, 1.0, v83
	v_rcp_f32_e32 v80, v80
	v_rcp_f32_e32 v81, v81
	v_rcp_f32_e32 v82, v82
	v_rcp_f32_e32 v83, v83
	v_mul_f32_e32 v36, v36, v80
	v_mul_f32_e32 v37, v37, v81
	v_mul_f32_e32 v38, v38, v82
	v_mul_f32_e32 v39, v39, v83
	v_cvt_pk_bf16_f32 v86, v36, v37
	v_cvt_pk_bf16_f32 v87, v38, v39
	global_store_short v[200:201], v86, off offset:64 sc0 sc1
	global_store_short_d16_hi v[200:201], v86, off offset:704 sc0 sc1
	global_store_short v[200:201], v87, off offset:1344 sc0 sc1
	global_store_short_d16_hi v[200:201], v87, off offset:1984 sc0 sc1
	v_add_f32_e32 v40, v40, v68
	v_add_f32_e32 v41, v41, v68
	v_add_f32_e32 v42, v42, v68
	v_add_f32_e32 v43, v43, v68
	v_mul_f32_e32 v80, 0xbfb8aa3b, v40
	v_mul_f32_e32 v81, 0xbfb8aa3b, v41
	v_mul_f32_e32 v82, 0xbfb8aa3b, v42
	v_mul_f32_e32 v83, 0xbfb8aa3b, v43
	v_exp_f32_e32 v80, v80
	v_exp_f32_e32 v81, v81
	v_exp_f32_e32 v82, v82
	v_exp_f32_e32 v83, v83
	v_add_f32_e32 v80, 1.0, v80
	v_add_f32_e32 v81, 1.0, v81
	v_add_f32_e32 v82, 1.0, v82
	v_add_f32_e32 v83, 1.0, v83
	v_rcp_f32_e32 v80, v80
	v_rcp_f32_e32 v81, v81
	v_rcp_f32_e32 v82, v82
	v_rcp_f32_e32 v83, v83
	v_mul_f32_e32 v40, v40, v80
	v_mul_f32_e32 v41, v41, v81
	v_mul_f32_e32 v42, v42, v82
	v_mul_f32_e32 v43, v43, v83
	v_cvt_pk_bf16_f32 v88, v40, v41
	v_cvt_pk_bf16_f32 v89, v42, v43
	global_store_short v[202:203], v88, off offset:64 sc0 sc1
	global_store_short_d16_hi v[202:203], v88, off offset:704 sc0 sc1
	global_store_short v[202:203], v89, off offset:1344 sc0 sc1
	global_store_short_d16_hi v[202:203], v89, off offset:1984 sc0 sc1
	v_add_f32_e32 v44, v44, v68
	v_add_f32_e32 v45, v45, v68
	v_add_f32_e32 v46, v46, v68
	v_add_f32_e32 v47, v47, v68
	v_mul_f32_e32 v80, 0xbfb8aa3b, v44
	v_mul_f32_e32 v81, 0xbfb8aa3b, v45
	v_mul_f32_e32 v82, 0xbfb8aa3b, v46
	v_mul_f32_e32 v83, 0xbfb8aa3b, v47
	v_exp_f32_e32 v80, v80
	v_exp_f32_e32 v81, v81
	v_exp_f32_e32 v82, v82
	v_exp_f32_e32 v83, v83
	v_add_f32_e32 v80, 1.0, v80
	v_add_f32_e32 v81, 1.0, v81
	v_add_f32_e32 v82, 1.0, v82
	v_add_f32_e32 v83, 1.0, v83
	v_rcp_f32_e32 v80, v80
	v_rcp_f32_e32 v81, v81
	v_rcp_f32_e32 v82, v82
	v_rcp_f32_e32 v83, v83
	v_mul_f32_e32 v44, v44, v80
	v_mul_f32_e32 v45, v45, v81
	v_mul_f32_e32 v46, v46, v82
	v_mul_f32_e32 v47, v47, v83
	v_cvt_pk_bf16_f32 v90, v44, v45
	v_cvt_pk_bf16_f32 v91, v46, v47
	global_store_short v[204:205], v90, off offset:64 sc0 sc1
	global_store_short_d16_hi v[204:205], v90, off offset:704 sc0 sc1
	global_store_short v[204:205], v91, off offset:1344 sc0 sc1
	global_store_short_d16_hi v[204:205], v91, off offset:1984 sc0 sc1
	v_add_f32_e32 v16, v16, v69
	v_add_f32_e32 v17, v17, v69
	v_add_f32_e32 v18, v18, v69
	v_add_f32_e32 v19, v19, v69
	v_mul_f32_e32 v80, 0xbfb8aa3b, v16
	v_mul_f32_e32 v81, 0xbfb8aa3b, v17
	v_mul_f32_e32 v82, 0xbfb8aa3b, v18
	v_mul_f32_e32 v83, 0xbfb8aa3b, v19
	v_exp_f32_e32 v80, v80
	v_exp_f32_e32 v81, v81
	v_exp_f32_e32 v82, v82
	v_exp_f32_e32 v83, v83
	v_add_f32_e32 v80, 1.0, v80
	v_add_f32_e32 v81, 1.0, v81
	v_add_f32_e32 v82, 1.0, v82
	v_add_f32_e32 v83, 1.0, v83
	v_rcp_f32_e32 v80, v80
	v_rcp_f32_e32 v81, v81
	v_rcp_f32_e32 v82, v82
	v_rcp_f32_e32 v83, v83
	v_mul_f32_e32 v16, v16, v80
	v_mul_f32_e32 v17, v17, v81
	v_mul_f32_e32 v18, v18, v82
	v_mul_f32_e32 v19, v19, v83
	v_cvt_pk_bf16_f32 v84, v16, v17
	v_cvt_pk_bf16_f32 v85, v18, v19
	global_store_short v[206:207], v84, off sc0 sc1
	global_store_short_d16_hi v[206:207], v84, off offset:640 sc0 sc1
	global_store_short v[206:207], v85, off offset:1280 sc0 sc1
	global_store_short_d16_hi v[206:207], v85, off offset:1920 sc0 sc1
	v_add_f32_e32 v20, v20, v69
	v_add_f32_e32 v21, v21, v69
	v_add_f32_e32 v22, v22, v69
	v_add_f32_e32 v23, v23, v69
	v_mul_f32_e32 v80, 0xbfb8aa3b, v20
	v_mul_f32_e32 v81, 0xbfb8aa3b, v21
	v_mul_f32_e32 v82, 0xbfb8aa3b, v22
	v_mul_f32_e32 v83, 0xbfb8aa3b, v23
	v_exp_f32_e32 v80, v80
	v_exp_f32_e32 v81, v81
	v_exp_f32_e32 v82, v82
	v_exp_f32_e32 v83, v83
	v_add_f32_e32 v80, 1.0, v80
	v_add_f32_e32 v81, 1.0, v81
	v_add_f32_e32 v82, 1.0, v82
	v_add_f32_e32 v83, 1.0, v83
	v_rcp_f32_e32 v80, v80
	v_rcp_f32_e32 v81, v81
	v_rcp_f32_e32 v82, v82
	v_rcp_f32_e32 v83, v83
	v_mul_f32_e32 v20, v20, v80
	v_mul_f32_e32 v21, v21, v81
	v_mul_f32_e32 v22, v22, v82
	v_mul_f32_e32 v23, v23, v83
	v_cvt_pk_bf16_f32 v86, v20, v21
	v_cvt_pk_bf16_f32 v87, v22, v23
	global_store_short v[208:209], v86, off sc0 sc1
	global_store_short_d16_hi v[208:209], v86, off offset:640 sc0 sc1
	global_store_short v[208:209], v87, off offset:1280 sc0 sc1
	global_store_short_d16_hi v[208:209], v87, off offset:1920 sc0 sc1
	v_add_f32_e32 v24, v24, v69
	v_add_f32_e32 v25, v25, v69
	v_add_f32_e32 v26, v26, v69
	v_add_f32_e32 v27, v27, v69
	v_mul_f32_e32 v80, 0xbfb8aa3b, v24
	v_mul_f32_e32 v81, 0xbfb8aa3b, v25
	v_mul_f32_e32 v82, 0xbfb8aa3b, v26
	v_mul_f32_e32 v83, 0xbfb8aa3b, v27
	v_exp_f32_e32 v80, v80
	v_exp_f32_e32 v81, v81
	v_exp_f32_e32 v82, v82
	v_exp_f32_e32 v83, v83
	v_add_f32_e32 v80, 1.0, v80
	v_add_f32_e32 v81, 1.0, v81
	v_add_f32_e32 v82, 1.0, v82
	v_add_f32_e32 v83, 1.0, v83
	v_rcp_f32_e32 v80, v80
	v_rcp_f32_e32 v81, v81
	v_rcp_f32_e32 v82, v82
	v_rcp_f32_e32 v83, v83
	v_mul_f32_e32 v24, v24, v80
	v_mul_f32_e32 v25, v25, v81
	v_mul_f32_e32 v26, v26, v82
	v_mul_f32_e32 v27, v27, v83
	v_cvt_pk_bf16_f32 v88, v24, v25
	v_cvt_pk_bf16_f32 v89, v26, v27
	global_store_short v[210:211], v88, off sc0 sc1
	global_store_short_d16_hi v[210:211], v88, off offset:640 sc0 sc1
	global_store_short v[210:211], v89, off offset:1280 sc0 sc1
	global_store_short_d16_hi v[210:211], v89, off offset:1920 sc0 sc1
	v_add_f32_e32 v28, v28, v69
	v_add_f32_e32 v29, v29, v69
	v_add_f32_e32 v30, v30, v69
	v_add_f32_e32 v31, v31, v69
	v_mul_f32_e32 v80, 0xbfb8aa3b, v28
	v_mul_f32_e32 v81, 0xbfb8aa3b, v29
	v_mul_f32_e32 v82, 0xbfb8aa3b, v30
	v_mul_f32_e32 v83, 0xbfb8aa3b, v31
	v_exp_f32_e32 v80, v80
	v_exp_f32_e32 v81, v81
	v_exp_f32_e32 v82, v82
	v_exp_f32_e32 v83, v83
	v_add_f32_e32 v80, 1.0, v80
	v_add_f32_e32 v81, 1.0, v81
	v_add_f32_e32 v82, 1.0, v82
	v_add_f32_e32 v83, 1.0, v83
	v_rcp_f32_e32 v80, v80
	v_rcp_f32_e32 v81, v81
	v_rcp_f32_e32 v82, v82
	v_rcp_f32_e32 v83, v83
	v_mul_f32_e32 v28, v28, v80
	v_mul_f32_e32 v29, v29, v81
	v_mul_f32_e32 v30, v30, v82
	v_mul_f32_e32 v31, v31, v83
	v_cvt_pk_bf16_f32 v90, v28, v29
	v_cvt_pk_bf16_f32 v91, v30, v31
	global_store_short v[212:213], v90, off sc0 sc1
	global_store_short_d16_hi v[212:213], v90, off offset:640 sc0 sc1
	global_store_short v[212:213], v91, off offset:1280 sc0 sc1
	global_store_short_d16_hi v[212:213], v91, off offset:1920 sc0 sc1
	v_add_f32_e32 v0, v0, v68
	v_add_f32_e32 v1, v1, v68
	v_add_f32_e32 v2, v2, v68
	v_add_f32_e32 v3, v3, v68
	v_mul_f32_e32 v80, 0xbfb8aa3b, v0
	v_mul_f32_e32 v81, 0xbfb8aa3b, v1
	v_mul_f32_e32 v82, 0xbfb8aa3b, v2
	v_mul_f32_e32 v83, 0xbfb8aa3b, v3
	v_exp_f32_e32 v80, v80
	v_exp_f32_e32 v81, v81
	v_exp_f32_e32 v82, v82
	v_exp_f32_e32 v83, v83
	v_add_f32_e32 v80, 1.0, v80
	v_add_f32_e32 v81, 1.0, v81
	v_add_f32_e32 v82, 1.0, v82
	v_add_f32_e32 v83, 1.0, v83
	v_rcp_f32_e32 v80, v80
	v_rcp_f32_e32 v81, v81
	v_rcp_f32_e32 v82, v82
	v_rcp_f32_e32 v83, v83
	v_mul_f32_e32 v0, v0, v80
	v_mul_f32_e32 v1, v1, v81
	v_mul_f32_e32 v2, v2, v82
	v_mul_f32_e32 v3, v3, v83
	v_cvt_pk_bf16_f32 v84, v0, v1
	v_cvt_pk_bf16_f32 v85, v2, v3
	global_store_short v[206:207], v84, off offset:64 sc0 sc1
	global_store_short_d16_hi v[206:207], v84, off offset:704 sc0 sc1
	global_store_short v[206:207], v85, off offset:1344 sc0 sc1
	global_store_short_d16_hi v[206:207], v85, off offset:1984 sc0 sc1
	v_add_f32_e32 v4, v4, v68
	v_add_f32_e32 v5, v5, v68
	v_add_f32_e32 v6, v6, v68
	v_add_f32_e32 v7, v7, v68
	v_mul_f32_e32 v80, 0xbfb8aa3b, v4
	v_mul_f32_e32 v81, 0xbfb8aa3b, v5
	v_mul_f32_e32 v82, 0xbfb8aa3b, v6
	v_mul_f32_e32 v83, 0xbfb8aa3b, v7
	v_exp_f32_e32 v80, v80
	v_exp_f32_e32 v81, v81
	v_exp_f32_e32 v82, v82
	v_exp_f32_e32 v83, v83
	v_add_f32_e32 v80, 1.0, v80
	v_add_f32_e32 v81, 1.0, v81
	v_add_f32_e32 v82, 1.0, v82
	v_add_f32_e32 v83, 1.0, v83
	v_rcp_f32_e32 v80, v80
	v_rcp_f32_e32 v81, v81
	v_rcp_f32_e32 v82, v82
	v_rcp_f32_e32 v83, v83
	v_mul_f32_e32 v4, v4, v80
	v_mul_f32_e32 v5, v5, v81
	v_mul_f32_e32 v6, v6, v82
	v_mul_f32_e32 v7, v7, v83
	v_cvt_pk_bf16_f32 v86, v4, v5
	v_cvt_pk_bf16_f32 v87, v6, v7
	global_store_short v[208:209], v86, off offset:64 sc0 sc1
	global_store_short_d16_hi v[208:209], v86, off offset:704 sc0 sc1
	global_store_short v[208:209], v87, off offset:1344 sc0 sc1
	global_store_short_d16_hi v[208:209], v87, off offset:1984 sc0 sc1
	v_add_f32_e32 v8, v8, v68
	v_add_f32_e32 v9, v9, v68
	v_add_f32_e32 v10, v10, v68
	v_add_f32_e32 v11, v11, v68
	v_mul_f32_e32 v80, 0xbfb8aa3b, v8
	v_mul_f32_e32 v81, 0xbfb8aa3b, v9
	v_mul_f32_e32 v82, 0xbfb8aa3b, v10
	v_mul_f32_e32 v83, 0xbfb8aa3b, v11
	v_exp_f32_e32 v80, v80
	v_exp_f32_e32 v81, v81
	v_exp_f32_e32 v82, v82
	v_exp_f32_e32 v83, v83
	v_add_f32_e32 v80, 1.0, v80
	v_add_f32_e32 v81, 1.0, v81
	v_add_f32_e32 v82, 1.0, v82
	v_add_f32_e32 v83, 1.0, v83
	v_rcp_f32_e32 v80, v80
	v_rcp_f32_e32 v81, v81
	v_rcp_f32_e32 v82, v82
	v_rcp_f32_e32 v83, v83
	v_mul_f32_e32 v8, v8, v80
	v_mul_f32_e32 v9, v9, v81
	v_mul_f32_e32 v10, v10, v82
	v_mul_f32_e32 v11, v11, v83
	v_cvt_pk_bf16_f32 v88, v8, v9
	v_cvt_pk_bf16_f32 v89, v10, v11
	global_store_short v[210:211], v88, off offset:64 sc0 sc1
	global_store_short_d16_hi v[210:211], v88, off offset:704 sc0 sc1
	global_store_short v[210:211], v89, off offset:1344 sc0 sc1
	global_store_short_d16_hi v[210:211], v89, off offset:1984 sc0 sc1
	v_add_f32_e32 v12, v12, v68
	v_add_f32_e32 v13, v13, v68
	v_add_f32_e32 v14, v14, v68
	v_add_f32_e32 v15, v15, v68
	v_mul_f32_e32 v80, 0xbfb8aa3b, v12
	v_mul_f32_e32 v81, 0xbfb8aa3b, v13
	v_mul_f32_e32 v82, 0xbfb8aa3b, v14
	v_mul_f32_e32 v83, 0xbfb8aa3b, v15
	v_exp_f32_e32 v80, v80
	v_exp_f32_e32 v81, v81
	v_exp_f32_e32 v82, v82
	v_exp_f32_e32 v83, v83
	v_add_f32_e32 v80, 1.0, v80
	v_add_f32_e32 v81, 1.0, v81
	v_add_f32_e32 v82, 1.0, v82
	v_add_f32_e32 v83, 1.0, v83
	v_rcp_f32_e32 v80, v80
	v_rcp_f32_e32 v81, v81
	v_rcp_f32_e32 v82, v82
	v_rcp_f32_e32 v83, v83
	v_mul_f32_e32 v12, v12, v80
	v_mul_f32_e32 v13, v13, v81
	v_mul_f32_e32 v14, v14, v82
	v_mul_f32_e32 v15, v15, v83
	v_cvt_pk_bf16_f32 v90, v12, v13
	v_cvt_pk_bf16_f32 v91, v14, v15
	global_store_short v[212:213], v90, off offset:64 sc0 sc1
	global_store_short_d16_hi v[212:213], v90, off offset:704 sc0 sc1
	global_store_short v[212:213], v91, off offset:1344 sc0 sc1
	global_store_short_d16_hi v[212:213], v91, off offset:1984 sc0 sc1
	s_waitcnt lgkmcnt(0)
	s_barrier
	s_waitcnt vmcnt(0)
	s_barrier
	s_mov_b64 s[4:5], exec
	v_readlane_b32 s0, v254, 29
	v_readlane_b32 s1, v254, 30
	s_and_b64 s[0:1], s[4:5], s[0:1]
	s_mov_b64 exec, s[0:1]
	s_cbranch_execz .Lc2_pub_done
	v_mov_b32_e32 v0, 0
	v_mov_b32_e32 v1, 1
	global_atomic_add v0, v1, s[68:69] offset:160

.Lc2_spun:
.Lc2_wait_done:
	s_mov_b64 exec, s[4:5]
	s_barrier
	v_readlane_b32 s2, v255, 12
	s_lshr_b32 s4, s2, 1
	s_and_b32 s4, s4, 15
	s_lshr_b32 s0, s2, 5
	s_lshl_b32 s0, s0, 4
	s_or_b32 s4, s4, s0
	s_or_b32 s4, s4, 0x100
	s_mov_b64 s[6:7], -1
	s_branch .Lcmp2_entry
